# EpiGate epilogue: P-tile loads prefetched one block ahead into spare VGPRs (counted vmcnt)
# speedup vs baseline: 1.0645x; 1.0039x over previous
; __device__ __forceinline__ unsigned cvt_pk_bf16(float lo, float hi) { f32x2_t v = {lo, hi}; bf2_t r = __builtin_convertvector(v, bf2_t); return __builtin_bit_cast(unsigned, r); }
; __device__ __forceinline__ float bflo(unsigned u) { return __uint_as_float(u << 16); }
; __device__ __forceinline__ float bfhi(unsigned u) { return __uint_as_float(u & 0xffff0000u); }
; __device__ __forceinline__ float sigmoidf_(float x) { return 1.0f / (1.0f + __expf(-x)); }
;     __device__ __forceinline__ void operator()(const f32x4 (&acc)[2][2][4][2], const Unit& u, int wr, int wc, int fr, int fq) const {
;     ...
;             for (int m2 = 0; m2 < 2; ++m2) {
;                 u32x4 pvv[2][2], ovv[2][2];
; #pragma unroll
;                 for (int mm = 0; mm < 2; ++mm) { const size_t row = (size_t)(row0 + ai * HALF + (2 * m2 + mm) * 16);
; #pragma unroll
;                     for (int bj = 0; bj < 2; ++bj) { pvv[mm][bj] = *(const u32x4*)(P + row * 4096 + colg + bj * HALF);
;                         if (j > 0) ovv[mm][bj] = *(const u32x4*)(mixed + row * 1024 + colm + bj * HALF); else ovv[mm][bj] = (u32x4){0u, 0u, 0u, 0u}; } }
; #pragma unroll
;                 for (int mm = 0; mm < 2; ++mm) { const int m = 2 * m2 + mm; const size_t row = (size_t)(row0 + ai * HALF + m * 16);
; #pragma unroll
;                     for (int bj = 0; bj < 2; ++bj) {
;                         const u32x4 pv = pvv[mm][bj], ov = ovv[mm][bj];
;                         bf16_t* mp = mixed + row * 1024 + colm + bj * HALF;
;                         const f32x4 a0 = acc[ai][bj][m][0] + bv[bj][0], a1 = acc[ai][bj][m][1] + bv[bj][1];
;                         float r[8];
;                         r[0] = sigmoidf_(a0[0]) * bflo(pv.x); r[1] = sigmoidf_(a0[1]) * bfhi(pv.x); r[2] = sigmoidf_(a0[2]) * bflo(pv.y); r[3] = sigmoidf_(a0[3]) * bfhi(pv.y);
;                         r[4] = sigmoidf_(a1[0]) * bflo(pv.z); r[5] = sigmoidf_(a1[1]) * bfhi(pv.z); r[6] = sigmoidf_(a1[2]) * bflo(pv.w); r[7] = sigmoidf_(a1[3]) * bfhi(pv.w);
;                         r[0] += bflo(ov.x); r[1] += bfhi(ov.x); r[2] += bflo(ov.y); r[3] += bfhi(ov.y); r[4] += bflo(ov.z); r[5] += bfhi(ov.z); r[6] += bflo(ov.w); r[7] += bfhi(ov.w);
;                         u32x4 w; w.x = cvt_pk_bf16(r[0], r[1]); w.y = cvt_pk_bf16(r[2], r[3]); w.z = cvt_pk_bf16(r[4], r[5]); w.w = cvt_pk_bf16(r[6], r[7]);
;                         *(u32x4*)mp = w; } }
.LBB0_909:
	v_or_b32_e32 v236, 32, v206
	v_ashrrev_i32_e32 v237, 31, v236
	v_lshlrev_b64 v[236:237], 13, v[236:237]
	v_lshl_add_u64 v[236:237], v[204:205], 0, v[236:237]
	global_load_dwordx4 v[188:191], v[236:237], off
	global_load_dwordx4 v[232:235], v[236:237], off offset:256
	v_or_b32_e32 v248, 48, v206
	v_ashrrev_i32_e32 v249, 31, v248
	v_lshlrev_b64 v[248:249], 13, v[248:249]
	v_lshl_add_u64 v[248:249], v[204:205], 0, v[248:249]
	global_load_dwordx4 v[240:243], v[248:249], off
	global_load_dwordx4 v[244:247], v[248:249], off offset:256
	s_waitcnt vmcnt(4)
	v_pk_add_f32 v[166:167], v[166:167], v[40:41]
	v_pk_add_f32 v[162:163], v[162:163], v[32:33]
	v_mul_f32_e32 v166, 0xbfb8aa3b, v166
	v_mul_f32_e32 v167, 0xbfb8aa3b, v167
	v_exp_f32_e32 v166, v166
	v_exp_f32_e32 v167, v167
	v_lshl_add_u64 v[178:179], s[6:7], 0, v[212:213]
	v_mul_f32_e32 v162, 0xbfb8aa3b, v162
	v_lshl_add_u64 v[212:213], v[178:179], 0, v[64:65]
	v_pk_add_f32 v[164:165], v[164:165], v[34:35]
	v_exp_f32_e32 v178, v162
	v_mul_f32_e32 v162, 0xbfb8aa3b, v163
	v_exp_f32_e32 v179, v162
	v_mul_f32_e32 v162, 0xbfb8aa3b, v164
	v_mul_f32_e32 v163, 0xbfb8aa3b, v165
	v_pk_add_f32 v[164:165], v[166:167], 1.0 op_sel_hi:[1,0]
	v_pk_add_f32 v[168:169], v[168:169], v[42:43]
	v_mul_f32_e32 v168, 0xbfb8aa3b, v168
	v_mul_f32_e32 v169, 0xbfb8aa3b, v169
	v_exp_f32_e32 v168, v168
	v_rcp_f32_e32 v165, v165
	v_exp_f32_e32 v169, v169
	v_exp_f32_e32 v162, v162
	v_exp_f32_e32 v163, v163
	v_rcp_f32_e32 v164, v164
	v_lshlrev_b32_e32 v166, 16, v170
	v_and_b32_e32 v167, 0xffff0000, v170
	v_lshlrev_b32_e32 v180, 16, v174
	v_and_b32_e32 v181, 0xffff0000, v174
	v_pk_fma_f32 v[164:165], v[164:165], v[166:167], v[180:181]
	v_pk_add_f32 v[166:167], v[168:169], 1.0 op_sel_hi:[1,0]
	v_pk_add_f32 v[162:163], v[162:163], 1.0 op_sel_hi:[1,0]
	v_pk_add_f32 v[142:143], v[142:143], v[28:29]
	v_pk_add_f32 v[138:139], v[138:139], v[24:25]
	v_mul_f32_e32 v142, 0xbfb8aa3b, v142
	v_rcp_f32_e32 v167, v167
	v_mul_f32_e32 v143, 0xbfb8aa3b, v143
	v_exp_f32_e32 v142, v142
	v_exp_f32_e32 v143, v143
	v_rcp_f32_e32 v166, v166
	v_lshlrev_b32_e32 v168, 16, v171
	v_and_b32_e32 v169, 0xffff0000, v171
	v_lshlrev_b32_e32 v170, 16, v175
	v_and_b32_e32 v171, 0xffff0000, v175
	v_pk_fma_f32 v[166:167], v[166:167], v[168:169], v[170:171]
	v_pk_add_f32 v[168:169], v[178:179], 1.0 op_sel_hi:[1,0]
	v_mul_f32_e32 v138, 0xbfb8aa3b, v138
	v_pk_add_f32 v[140:141], v[140:141], v[26:27]
	v_pk_add_f32 v[144:145], v[144:145], v[30:31]
	v_pk_add_f32 v[126:127], v[126:127], v[40:41]
	v_rcp_f32_e32 v169, v169
	v_mul_f32_e32 v144, 0xbfb8aa3b, v144
	v_mul_f32_e32 v145, 0xbfb8aa3b, v145
	v_exp_f32_e32 v144, v144
	v_rcp_f32_e32 v168, v168
	v_lshlrev_b32_e32 v170, 16, v172
	v_and_b32_e32 v171, 0xffff0000, v172
	v_lshlrev_b32_e32 v174, 16, v176
	v_and_b32_e32 v175, 0xffff0000, v176
	v_pk_fma_f32 v[168:169], v[168:169], v[170:171], v[174:175]
	v_exp_f32_e32 v145, v145
	v_mul_f32_e32 v126, 0xbfb8aa3b, v126
	v_mul_f32_e32 v127, 0xbfb8aa3b, v127
	v_rcp_f32_e32 v163, v163
	v_exp_f32_e32 v126, v126
	v_exp_f32_e32 v127, v127
	v_pk_add_f32 v[122:123], v[122:123], v[32:33]
	v_rcp_f32_e32 v162, v162
	v_lshlrev_b32_e32 v170, 16, v173
	v_and_b32_e32 v171, 0xffff0000, v173
	v_lshlrev_b32_e32 v172, 16, v177
	v_and_b32_e32 v173, 0xffff0000, v177
	v_pk_fma_f32 v[170:171], v[162:163], v[170:171], v[172:173]
	v_cvt_pk_bf16_f32 v162, v164, v165
	v_cvt_pk_bf16_f32 v163, v166, v167
	v_cvt_pk_bf16_f32 v164, v168, v169
	v_cvt_pk_bf16_f32 v165, v170, v171
	global_store_dwordx4 v[212:213], v[162:165], off
	v_mul_f32_e32 v122, 0xbfb8aa3b, v122
	v_pk_add_f32 v[124:125], v[124:125], v[34:35]
	v_exp_f32_e32 v162, v138
	v_mul_f32_e32 v138, 0xbfb8aa3b, v139
	v_exp_f32_e32 v163, v138
	v_mul_f32_e32 v138, 0xbfb8aa3b, v140
	v_mul_f32_e32 v139, 0xbfb8aa3b, v141
	v_pk_add_f32 v[140:141], v[142:143], 1.0 op_sel_hi:[1,0]
	v_exp_f32_e32 v138, v138
	v_exp_f32_e32 v139, v139
	v_pk_add_f32 v[128:129], v[128:129], v[42:43]
	v_pk_add_f32 v[118:119], v[118:119], v[28:29]
	v_rcp_f32_e32 v141, v141
	v_pk_add_f32 v[138:139], v[138:139], 1.0 op_sel_hi:[1,0]
	v_mul_f32_e32 v128, 0xbfb8aa3b, v128
	v_mul_f32_e32 v129, 0xbfb8aa3b, v129
	v_rcp_f32_e32 v140, v140
	v_lshlrev_b32_e32 v142, 16, v158
	v_and_b32_e32 v143, 0xffff0000, v158
	v_lshlrev_b32_e32 v164, 16, v154
	v_and_b32_e32 v165, 0xffff0000, v154
	v_pk_fma_f32 v[140:141], v[140:141], v[142:143], v[164:165]
	v_pk_add_f32 v[142:143], v[144:145], 1.0 op_sel_hi:[1,0]
	v_exp_f32_e32 v128, v128
	v_exp_f32_e32 v129, v129
	v_mul_f32_e32 v118, 0xbfb8aa3b, v118
	v_mul_f32_e32 v119, 0xbfb8aa3b, v119
	v_rcp_f32_e32 v143, v143
	v_exp_f32_e32 v118, v118
	v_exp_f32_e32 v119, v119
	v_pk_add_f32 v[114:115], v[114:115], v[24:25]
	v_rcp_f32_e32 v142, v142
	v_lshlrev_b32_e32 v144, 16, v159
	v_and_b32_e32 v145, 0xffff0000, v159
	v_lshlrev_b32_e32 v154, 16, v155
	v_and_b32_e32 v155, 0xffff0000, v155
	v_pk_fma_f32 v[142:143], v[142:143], v[144:145], v[154:155]
	v_pk_add_f32 v[144:145], v[162:163], 1.0 op_sel_hi:[1,0]
	v_mul_f32_e32 v114, 0xbfb8aa3b, v114
	v_pk_add_f32 v[116:117], v[116:117], v[26:27]
	v_pk_add_f32 v[120:121], v[120:121], v[30:31]
	v_rcp_f32_e32 v145, v145
	v_mul_f32_e32 v120, 0xbfb8aa3b, v120
	v_mul_f32_e32 v121, 0xbfb8aa3b, v121
	v_exp_f32_e32 v120, v120
	v_rcp_f32_e32 v144, v144
	v_lshlrev_b32_e32 v154, 16, v160
	v_and_b32_e32 v155, 0xffff0000, v160
	v_lshlrev_b32_e32 v158, 16, v156
	v_and_b32_e32 v159, 0xffff0000, v156
	v_pk_fma_f32 v[144:145], v[144:145], v[154:155], v[158:159]
	v_exp_f32_e32 v121, v121
	v_rcp_f32_e32 v139, v139
	s_nop 0
	v_rcp_f32_e32 v138, v138
	v_lshlrev_b32_e32 v154, 16, v161
	v_and_b32_e32 v155, 0xffff0000, v161
; __device__ __forceinline__ unsigned cvt_pk_bf16(float lo, float hi) { f32x2_t v = {lo, hi}; bf2_t r = __builtin_convertvector(v, bf2_t); return __builtin_bit_cast(unsigned, r); }
; __device__ __forceinline__ float bflo(unsigned u) { return __uint_as_float(u << 16); }
; __device__ __forceinline__ float bfhi(unsigned u) { return __uint_as_float(u & 0xffff0000u); }
; __device__ __forceinline__ float sigmoidf_(float x) { return 1.0f / (1.0f + __expf(-x)); }
;     __device__ __forceinline__ void operator()(const f32x4 (&acc)[2][2][4][2], const Unit& u, int wr, int wc, int fr, int fq) const {
;     ...
;             for (int m2 = 0; m2 < 2; ++m2) {
;                 u32x4 pvv[2][2], ovv[2][2];
; #pragma unroll
;                 for (int mm = 0; mm < 2; ++mm) { const size_t row = (size_t)(row0 + ai * HALF + (2 * m2 + mm) * 16);
; #pragma unroll
;                     for (int bj = 0; bj < 2; ++bj) { pvv[mm][bj] = *(const u32x4*)(P + row * 4096 + colg + bj * HALF);
;                         if (j > 0) ovv[mm][bj] = *(const u32x4*)(mixed + row * 1024 + colm + bj * HALF); else ovv[mm][bj] = (u32x4){0u, 0u, 0u, 0u}; } }
; #pragma unroll
;                 for (int mm = 0; mm < 2; ++mm) { const int m = 2 * m2 + mm; const size_t row = (size_t)(row0 + ai * HALF + m * 16);
; #pragma unroll
;                     for (int bj = 0; bj < 2; ++bj) {
;                         const u32x4 pv = pvv[mm][bj], ov = ovv[mm][bj];
;                         bf16_t* mp = mixed + row * 1024 + colm + bj * HALF;
;                         const f32x4 a0 = acc[ai][bj][m][0] + bv[bj][0], a1 = acc[ai][bj][m][1] + bv[bj][1];
;                         float r[8];
;                         r[0] = sigmoidf_(a0[0]) * bflo(pv.x); r[1] = sigmoidf_(a0[1]) * bfhi(pv.x); r[2] = sigmoidf_(a0[2]) * bflo(pv.y); r[3] = sigmoidf_(a0[3]) * bfhi(pv.y);
;                         r[4] = sigmoidf_(a1[0]) * bflo(pv.z); r[5] = sigmoidf_(a1[1]) * bfhi(pv.z); r[6] = sigmoidf_(a1[2]) * bflo(pv.w); r[7] = sigmoidf_(a1[3]) * bfhi(pv.w);
;                         r[0] += bflo(ov.x); r[1] += bfhi(ov.x); r[2] += bflo(ov.y); r[3] += bfhi(ov.y); r[4] += bflo(ov.z); r[5] += bfhi(ov.z); r[6] += bflo(ov.w); r[7] += bfhi(ov.w);
;                         u32x4 w; w.x = cvt_pk_bf16(r[0], r[1]); w.y = cvt_pk_bf16(r[2], r[3]); w.z = cvt_pk_bf16(r[4], r[5]); w.w = cvt_pk_bf16(r[6], r[7]);
;                         *(u32x4*)mp = w; } }
	v_lshlrev_b32_e32 v156, 16, v157
	v_and_b32_e32 v157, 0xffff0000, v157
	v_pk_fma_f32 v[154:155], v[138:139], v[154:155], v[156:157]
	v_cvt_pk_bf16_f32 v138, v140, v141
	v_cvt_pk_bf16_f32 v139, v142, v143
	v_cvt_pk_bf16_f32 v140, v144, v145
	v_cvt_pk_bf16_f32 v141, v154, v155
	global_store_dwordx4 v[212:213], v[138:141], off offset:256
	v_mov_b32_e32 v145, 0
	s_nop 0
	v_exp_f32_e32 v140, v122
	v_mul_f32_e32 v122, 0xbfb8aa3b, v123
	v_exp_f32_e32 v141, v122
	v_mul_f32_e32 v122, 0xbfb8aa3b, v124
	v_mul_f32_e32 v123, 0xbfb8aa3b, v125
	v_pk_add_f32 v[124:125], v[126:127], 1.0 op_sel_hi:[1,0]
	v_exp_f32_e32 v122, v122
	v_exp_f32_e32 v123, v123
	v_lshl_add_u64 v[138:139], s[6:7], 0, v[210:211]
	v_lshl_add_u64 v[138:139], v[138:139], 0, v[64:65]
	v_rcp_f32_e32 v125, v125
	v_pk_add_f32 v[122:123], v[122:123], 1.0 op_sel_hi:[1,0]
	v_rcp_f32_e32 v124, v124
	v_lshlrev_b32_e32 v126, 16, v146
	v_and_b32_e32 v127, 0xffff0000, v146
	v_lshlrev_b32_e32 v142, 16, v150
	v_and_b32_e32 v143, 0xffff0000, v150
	v_pk_fma_f32 v[124:125], v[124:125], v[126:127], v[142:143]
	v_pk_add_f32 v[126:127], v[128:129], 1.0 op_sel_hi:[1,0]
	s_nop 0
	s_nop 0
	v_rcp_f32_e32 v127, v127
	s_nop 0
	v_rcp_f32_e32 v126, v126
	v_lshlrev_b32_e32 v128, 16, v147
	v_and_b32_e32 v129, 0xffff0000, v147
	v_lshlrev_b32_e32 v142, 16, v151
	v_and_b32_e32 v143, 0xffff0000, v151
	v_pk_fma_f32 v[126:127], v[126:127], v[128:129], v[142:143]
	v_pk_add_f32 v[128:129], v[140:141], 1.0 op_sel_hi:[1,0]
	s_nop 0
	s_nop 0
	v_rcp_f32_e32 v129, v129
	s_nop 0
	v_rcp_f32_e32 v128, v128
	v_lshlrev_b32_e32 v140, 16, v148
	v_and_b32_e32 v141, 0xffff0000, v148
	v_lshlrev_b32_e32 v142, 16, v152
	v_and_b32_e32 v143, 0xffff0000, v152
	v_pk_fma_f32 v[128:129], v[128:129], v[140:141], v[142:143]
	s_nop 0
	v_rcp_f32_e32 v123, v123
	s_nop 0
	v_rcp_f32_e32 v122, v122
	v_lshlrev_b32_e32 v140, 16, v149
	v_and_b32_e32 v141, 0xffff0000, v149
	v_lshlrev_b32_e32 v142, 16, v153
	v_and_b32_e32 v143, 0xffff0000, v153
	v_pk_fma_f32 v[140:141], v[122:123], v[140:141], v[142:143]
	v_cvt_pk_bf16_f32 v122, v124, v125
	v_cvt_pk_bf16_f32 v123, v126, v127
	v_cvt_pk_bf16_f32 v124, v128, v129
	v_cvt_pk_bf16_f32 v125, v140, v141
	global_store_dwordx4 v[138:139], v[122:125], off
	v_mov_b32_e32 v142, 0
	v_mov_b32_e32 v143, 0
	v_exp_f32_e32 v122, v114
	v_mul_f32_e32 v114, 0xbfb8aa3b, v115
	v_exp_f32_e32 v123, v114
	v_mul_f32_e32 v114, 0xbfb8aa3b, v116
	v_mul_f32_e32 v115, 0xbfb8aa3b, v117
	v_pk_add_f32 v[116:117], v[118:119], 1.0 op_sel_hi:[1,0]
	v_exp_f32_e32 v114, v114
	v_exp_f32_e32 v115, v115
	v_mov_b32_e32 v144, 0
	v_rcp_f32_e32 v117, v117
	v_pk_add_f32 v[114:115], v[114:115], 1.0 op_sel_hi:[1,0]
	v_rcp_f32_e32 v116, v116
	v_lshlrev_b32_e32 v118, 16, v134
	v_and_b32_e32 v119, 0xffff0000, v134
	v_lshlrev_b32_e32 v124, 16, v130
	v_and_b32_e32 v125, 0xffff0000, v130
	v_pk_fma_f32 v[116:117], v[116:117], v[118:119], v[124:125]
	v_pk_add_f32 v[118:119], v[120:121], 1.0 op_sel_hi:[1,0]
	v_mov_b32_e32 v130, 0
	s_nop 0
	v_rcp_f32_e32 v119, v119
	s_nop 0
	v_rcp_f32_e32 v118, v118
	v_lshlrev_b32_e32 v120, 16, v135
	v_and_b32_e32 v121, 0xffff0000, v135
	v_lshlrev_b32_e32 v124, 16, v131
	v_and_b32_e32 v125, 0xffff0000, v131
	v_pk_fma_f32 v[118:119], v[118:119], v[120:121], v[124:125]
	v_pk_add_f32 v[120:121], v[122:123], 1.0 op_sel_hi:[1,0]
	s_nop 0
	s_nop 0
	v_rcp_f32_e32 v121, v121
	s_nop 0
	v_rcp_f32_e32 v120, v120
	v_lshlrev_b32_e32 v122, 16, v136
	v_and_b32_e32 v123, 0xffff0000, v136
	v_lshlrev_b32_e32 v124, 16, v132
	v_and_b32_e32 v125, 0xffff0000, v132
	v_pk_fma_f32 v[120:121], v[120:121], v[122:123], v[124:125]
	s_nop 0
	v_rcp_f32_e32 v115, v115
	s_nop 0
	v_rcp_f32_e32 v114, v114
	v_lshlrev_b32_e32 v122, 16, v137
	v_and_b32_e32 v123, 0xffff0000, v137
	v_lshlrev_b32_e32 v124, 16, v133
	v_and_b32_e32 v125, 0xffff0000, v133
	v_pk_fma_f32 v[122:123], v[114:115], v[122:123], v[124:125]
	v_cvt_pk_bf16_f32 v114, v116, v117
	v_cvt_pk_bf16_f32 v115, v118, v119
	v_cvt_pk_bf16_f32 v116, v120, v121
	v_cvt_pk_bf16_f32 v117, v122, v123
	global_store_dwordx4 v[138:139], v[114:117], off offset:256
	s_and_b64 vcc, exec, s[42:43]
	s_nop 0
	v_or_b32_e32 v114, 32, v206
	v_ashrrev_i32_e32 v115, 31, v114
	v_lshlrev_b64 v[116:117], 13, v[114:115]
	v_lshl_add_u64 v[116:117], v[204:205], 0, v[116:117]
	s_waitcnt vmcnt(4)
	v_mov_b64_e32 v[138:139], v[188:189]
	v_mov_b64_e32 v[140:141], v[190:191]
	v_lshlrev_b64 v[148:149], 11, v[114:115]
	v_lshl_add_u64 v[114:115], v[208:209], 0, v[148:149]
	s_cbranch_vccnz .LBB0_911
	global_load_dwordx4 v[142:145], v[114:115], off
.LBB0_911:
	v_mov_b64_e32 v[134:135], v[232:233]
	v_mov_b64_e32 v[136:137], v[234:235]
	s_and_b64 vcc, exec, s[42:43]
	v_mov_b32_e32 v131, 0
	v_mov_b32_e32 v132, 0
	v_mov_b32_e32 v133, 0
	s_cbranch_vccnz .LBB0_913
	global_load_dwordx4 v[130:133], v[114:115], off offset:256
.LBB0_913:
	v_or_b32_e32 v114, 48, v206
	v_ashrrev_i32_e32 v115, 31, v114
	v_lshlrev_b64 v[116:117], 13, v[114:115]
	v_lshl_add_u64 v[116:117], v[204:205], 0, v[116:117]
	v_mov_b64_e32 v[122:123], v[240:241]
	v_mov_b64_e32 v[124:125], v[242:243]
	v_lshlrev_b64 v[146:147], 11, v[114:115]
	v_lshl_add_u64 v[150:151], v[208:209], 0, v[146:147]
	v_mov_b32_e32 v114, 0
	s_and_b64 vcc, exec, s[42:43]
	v_mov_b32_e32 v126, 0
	v_mov_b32_e32 v127, 0
	v_mov_b32_e32 v128, 0
	v_mov_b32_e32 v129, 0
	s_cbranch_vccnz .LBB0_915
	global_load_dwordx4 v[126:129], v[150:151], off
.LBB0_915:
	v_mov_b64_e32 v[118:119], v[244:245]
	v_mov_b64_e32 v[120:121], v[246:247]
	s_and_b64 vcc, exec, s[42:43]
	v_mov_b32_e32 v115, 0
	v_mov_b32_e32 v116, 0
	v_mov_b32_e32 v117, 0
	s_cbranch_vccnz .LBB0_917
	global_load_dwordx4 v[114:117], v[150:151], off offset:256
; __device__ __forceinline__ unsigned cvt_pk_bf16(float lo, float hi) { f32x2_t v = {lo, hi}; bf2_t r = __builtin_convertvector(v, bf2_t); return __builtin_bit_cast(unsigned, r); }
; __device__ __forceinline__ float bflo(unsigned u) { return __uint_as_float(u << 16); }
; __device__ __forceinline__ float bfhi(unsigned u) { return __uint_as_float(u & 0xffff0000u); }
; __device__ __forceinline__ float sigmoidf_(float x) { return 1.0f / (1.0f + __expf(-x)); }
;     __device__ __forceinline__ void operator()(const f32x4 (&acc)[2][2][4][2], const Unit& u, int wr, int wc, int fr, int fq) const {
;     ...
;                 for (int mm = 0; mm < 2; ++mm) { const size_t row = (size_t)(row0 + ai * HALF + (2 * m2 + mm) * 16);
; #pragma unroll
;                     for (int bj = 0; bj < 2; ++bj) { pvv[mm][bj] = *(const u32x4*)(P + row * 4096 + colg + bj * HALF);
;                         if (j > 0) ovv[mm][bj] = *(const u32x4*)(mixed + row * 1024 + colm + bj * HALF); else ovv[mm][bj] = (u32x4){0u, 0u, 0u, 0u}; } }
; #pragma unroll
;                 for (int mm = 0; mm < 2; ++mm) { const int m = 2 * m2 + mm; const size_t row = (size_t)(row0 + ai * HALF + m * 16);
; #pragma unroll
;                     for (int bj = 0; bj < 2; ++bj) {
;                         const u32x4 pv = pvv[mm][bj], ov = ovv[mm][bj];
;                         bf16_t* mp = mixed + row * 1024 + colm + bj * HALF;
;                         const f32x4 a0 = acc[ai][bj][m][0] + bv[bj][0], a1 = acc[ai][bj][m][1] + bv[bj][1];
;                         float r[8];
;                         r[0] = sigmoidf_(a0[0]) * bflo(pv.x); r[1] = sigmoidf_(a0[1]) * bfhi(pv.x); r[2] = sigmoidf_(a0[2]) * bflo(pv.y); r[3] = sigmoidf_(a0[3]) * bfhi(pv.y);
;                         r[4] = sigmoidf_(a1[0]) * bflo(pv.z); r[5] = sigmoidf_(a1[1]) * bfhi(pv.z); r[6] = sigmoidf_(a1[2]) * bflo(pv.w); r[7] = sigmoidf_(a1[3]) * bfhi(pv.w);
;                         r[0] += bflo(ov.x); r[1] += bfhi(ov.x); r[2] += bflo(ov.y); r[3] += bfhi(ov.y); r[4] += bflo(ov.z); r[5] += bfhi(ov.z); r[6] += bflo(ov.w); r[7] += bfhi(ov.w);
;                         u32x4 w; w.x = cvt_pk_bf16(r[0], r[1]); w.y = cvt_pk_bf16(r[2], r[3]); w.z = cvt_pk_bf16(r[4], r[5]); w.w = cvt_pk_bf16(r[6], r[7]);
;                         *(u32x4*)mp = w; } }
.LBB0_917:
	v_add_u32_e32 v236, 0x80, v206
	v_ashrrev_i32_e32 v237, 31, v236
	v_lshlrev_b64 v[236:237], 13, v[236:237]
	v_lshl_add_u64 v[236:237], v[204:205], 0, v[236:237]
	global_load_dwordx4 v[188:191], v[236:237], off
	global_load_dwordx4 v[232:235], v[236:237], off offset:256
	v_add_u32_e32 v248, 0x90, v206
	v_ashrrev_i32_e32 v249, 31, v248
	v_lshlrev_b64 v[248:249], 13, v[248:249]
	v_lshl_add_u64 v[248:249], v[204:205], 0, v[248:249]
	global_load_dwordx4 v[240:243], v[248:249], off
	global_load_dwordx4 v[244:247], v[248:249], off offset:256
	v_pk_add_f32 v[110:111], v[110:111], v[40:41]
	v_pk_add_f32 v[106:107], v[106:107], v[32:33]
	v_mul_f32_e32 v110, 0xbfb8aa3b, v110
	v_mul_f32_e32 v111, 0xbfb8aa3b, v111
	v_exp_f32_e32 v110, v110
	v_exp_f32_e32 v111, v111
	v_mul_f32_e32 v106, 0xbfb8aa3b, v106
	v_pk_add_f32 v[108:109], v[108:109], v[34:35]
	v_exp_f32_e32 v150, v106
	v_mul_f32_e32 v106, 0xbfb8aa3b, v107
	v_exp_f32_e32 v151, v106
	v_mul_f32_e32 v106, 0xbfb8aa3b, v108
	v_mul_f32_e32 v107, 0xbfb8aa3b, v109
	v_pk_add_f32 v[108:109], v[110:111], 1.0 op_sel_hi:[1,0]
	v_pk_add_f32 v[112:113], v[112:113], v[42:43]
	v_mul_f32_e32 v112, 0xbfb8aa3b, v112
	v_mul_f32_e32 v113, 0xbfb8aa3b, v113
	v_exp_f32_e32 v112, v112
	v_rcp_f32_e32 v109, v109
	v_exp_f32_e32 v113, v113
	v_exp_f32_e32 v106, v106
	v_exp_f32_e32 v107, v107
	v_rcp_f32_e32 v108, v108
	s_waitcnt vmcnt(7)
	v_lshlrev_b32_e32 v110, 16, v138
	v_and_b32_e32 v111, 0xffff0000, v138
	v_lshlrev_b32_e32 v152, 16, v142
	v_and_b32_e32 v153, 0xffff0000, v142
	v_pk_fma_f32 v[108:109], v[108:109], v[110:111], v[152:153]
	v_pk_add_f32 v[110:111], v[112:113], 1.0 op_sel_hi:[1,0]
	v_pk_add_f32 v[106:107], v[106:107], 1.0 op_sel_hi:[1,0]
	v_pk_add_f32 v[102:103], v[102:103], v[28:29]
	v_lshl_add_u64 v[148:149], s[6:7], 0, v[148:149]
	v_mul_f32_e32 v102, 0xbfb8aa3b, v102
	v_rcp_f32_e32 v111, v111
	v_mul_f32_e32 v103, 0xbfb8aa3b, v103
	v_exp_f32_e32 v102, v102
	v_exp_f32_e32 v103, v103
	v_rcp_f32_e32 v110, v110
	v_lshlrev_b32_e32 v112, 16, v139
	v_and_b32_e32 v113, 0xffff0000, v139
	v_lshlrev_b32_e32 v138, 16, v143
	v_and_b32_e32 v139, 0xffff0000, v143
	v_pk_fma_f32 v[110:111], v[110:111], v[112:113], v[138:139]
	v_pk_add_f32 v[112:113], v[150:151], 1.0 op_sel_hi:[1,0]
	v_pk_add_f32 v[98:99], v[98:99], v[24:25]
	v_lshl_add_u64 v[148:149], v[148:149], 0, v[64:65]
	v_mul_f32_e32 v98, 0xbfb8aa3b, v98
	v_pk_add_f32 v[100:101], v[100:101], v[26:27]
	v_rcp_f32_e32 v113, v113
	v_pk_add_f32 v[104:105], v[104:105], v[30:31]
	v_pk_add_f32 v[94:95], v[94:95], v[40:41]
	v_mul_f32_e32 v104, 0xbfb8aa3b, v104
	v_rcp_f32_e32 v112, v112
	v_lshlrev_b32_e32 v138, 16, v140
	v_and_b32_e32 v139, 0xffff0000, v140
	v_lshlrev_b32_e32 v142, 16, v144
	v_and_b32_e32 v143, 0xffff0000, v144
	v_pk_fma_f32 v[112:113], v[112:113], v[138:139], v[142:143]
	v_mul_f32_e32 v105, 0xbfb8aa3b, v105
	v_exp_f32_e32 v104, v104
	v_exp_f32_e32 v105, v105
	v_rcp_f32_e32 v107, v107
	v_mul_f32_e32 v94, 0xbfb8aa3b, v94
	v_mul_f32_e32 v95, 0xbfb8aa3b, v95
	v_exp_f32_e32 v94, v94
	v_rcp_f32_e32 v106, v106
	v_lshlrev_b32_e32 v138, 16, v141
	v_and_b32_e32 v139, 0xffff0000, v141
	v_lshlrev_b32_e32 v140, 16, v145
	v_and_b32_e32 v141, 0xffff0000, v145
	v_pk_fma_f32 v[138:139], v[106:107], v[138:139], v[140:141]
	v_cvt_pk_bf16_f32 v106, v108, v109
	v_cvt_pk_bf16_f32 v107, v110, v111
	v_cvt_pk_bf16_f32 v108, v112, v113
	v_cvt_pk_bf16_f32 v109, v138, v139
	global_store_dwordx4 v[148:149], v[106:109], off
	v_exp_f32_e32 v95, v95
	v_pk_add_f32 v[90:91], v[90:91], v[32:33]
	v_exp_f32_e32 v106, v98
	v_mul_f32_e32 v98, 0xbfb8aa3b, v99
	v_exp_f32_e32 v107, v98
	v_mul_f32_e32 v98, 0xbfb8aa3b, v100
	v_mul_f32_e32 v99, 0xbfb8aa3b, v101
	v_pk_add_f32 v[100:101], v[102:103], 1.0 op_sel_hi:[1,0]
	v_exp_f32_e32 v98, v98
	v_exp_f32_e32 v99, v99
	v_mul_f32_e32 v90, 0xbfb8aa3b, v90
	v_pk_add_f32 v[92:93], v[92:93], v[34:35]
	v_rcp_f32_e32 v101, v101
	v_pk_add_f32 v[98:99], v[98:99], 1.0 op_sel_hi:[1,0]
	v_pk_add_f32 v[96:97], v[96:97], v[42:43]
	v_pk_add_f32 v[86:87], v[86:87], v[28:29]
	v_rcp_f32_e32 v100, v100
	s_waitcnt vmcnt(7)
	v_lshlrev_b32_e32 v102, 16, v134
	v_and_b32_e32 v103, 0xffff0000, v134
	v_lshlrev_b32_e32 v108, 16, v130
	v_and_b32_e32 v109, 0xffff0000, v130
	v_pk_fma_f32 v[100:101], v[100:101], v[102:103], v[108:109]
	v_pk_add_f32 v[102:103], v[104:105], 1.0 op_sel_hi:[1,0]
	v_mul_f32_e32 v96, 0xbfb8aa3b, v96
	v_mul_f32_e32 v97, 0xbfb8aa3b, v97
	v_exp_f32_e32 v96, v96
	v_exp_f32_e32 v97, v97
	v_rcp_f32_e32 v103, v103
	v_mul_f32_e32 v86, 0xbfb8aa3b, v86
	v_mul_f32_e32 v87, 0xbfb8aa3b, v87
	v_exp_f32_e32 v86, v86
	v_rcp_f32_e32 v102, v102
	v_lshlrev_b32_e32 v104, 16, v135
	v_and_b32_e32 v105, 0xffff0000, v135
	v_lshlrev_b32_e32 v108, 16, v131
	v_and_b32_e32 v109, 0xffff0000, v131
	v_pk_fma_f32 v[102:103], v[102:103], v[104:105], v[108:109]
	v_pk_add_f32 v[104:105], v[106:107], 1.0 op_sel_hi:[1,0]
	v_exp_f32_e32 v87, v87
	v_pk_add_f32 v[82:83], v[82:83], v[24:25]
	v_pk_add_f32 v[84:85], v[84:85], v[26:27]
	v_mul_f32_e32 v82, 0xbfb8aa3b, v82
	v_rcp_f32_e32 v105, v105
	v_pk_add_f32 v[88:89], v[88:89], v[30:31]
	v_mov_b32_e32 v111, 0
	v_mul_f32_e32 v88, 0xbfb8aa3b, v88
	v_rcp_f32_e32 v104, v104
	v_lshlrev_b32_e32 v106, 16, v136
	v_and_b32_e32 v107, 0xffff0000, v136
	v_lshlrev_b32_e32 v108, 16, v132
	v_and_b32_e32 v109, 0xffff0000, v132
	v_pk_fma_f32 v[104:105], v[104:105], v[106:107], v[108:109]
	v_mul_f32_e32 v89, 0xbfb8aa3b, v89
	v_exp_f32_e32 v88, v88
	v_exp_f32_e32 v89, v89
	v_rcp_f32_e32 v99, v99
	v_mov_b32_e32 v112, 0
	v_mov_b32_e32 v113, 0
	v_rcp_f32_e32 v98, v98
	v_lshlrev_b32_e32 v106, 16, v137
	v_and_b32_e32 v107, 0xffff0000, v137
	v_lshlrev_b32_e32 v108, 16, v133
	v_and_b32_e32 v109, 0xffff0000, v133
	v_pk_fma_f32 v[106:107], v[98:99], v[106:107], v[108:109]
	v_cvt_pk_bf16_f32 v98, v100, v101
	v_cvt_pk_bf16_f32 v99, v102, v103
	v_cvt_pk_bf16_f32 v100, v104, v105
	v_cvt_pk_bf16_f32 v101, v106, v107
	global_store_dwordx4 v[148:149], v[98:101], off offset:256
	v_mov_b32_e32 v110, 0
	s_nop 0
	v_exp_f32_e32 v100, v90
	v_mul_f32_e32 v90, 0xbfb8aa3b, v91
	v_exp_f32_e32 v101, v90
	v_mul_f32_e32 v90, 0xbfb8aa3b, v92
	v_mul_f32_e32 v91, 0xbfb8aa3b, v93
	v_pk_add_f32 v[92:93], v[94:95], 1.0 op_sel_hi:[1,0]
	v_exp_f32_e32 v90, v90
	v_exp_f32_e32 v91, v91
	v_lshl_add_u64 v[98:99], s[6:7], 0, v[146:147]
	v_lshl_add_u64 v[98:99], v[98:99], 0, v[64:65]
	v_rcp_f32_e32 v93, v93
	v_pk_add_f32 v[90:91], v[90:91], 1.0 op_sel_hi:[1,0]
	v_rcp_f32_e32 v92, v92
	s_waitcnt vmcnt(7)
; __device__ __forceinline__ unsigned cvt_pk_bf16(float lo, float hi) { f32x2_t v = {lo, hi}; bf2_t r = __builtin_convertvector(v, bf2_t); return __builtin_bit_cast(unsigned, r); }
; __device__ __forceinline__ float bflo(unsigned u) { return __uint_as_float(u << 16); }
; __device__ __forceinline__ float bfhi(unsigned u) { return __uint_as_float(u & 0xffff0000u); }
; __device__ __forceinline__ float sigmoidf_(float x) { return 1.0f / (1.0f + __expf(-x)); }
;     __device__ __forceinline__ void operator()(const f32x4 (&acc)[2][2][4][2], const Unit& u, int wr, int wc, int fr, int fq) const {
;     ...
;                 for (int mm = 0; mm < 2; ++mm) { const size_t row = (size_t)(row0 + ai * HALF + (2 * m2 + mm) * 16);
; #pragma unroll
;                     for (int bj = 0; bj < 2; ++bj) { pvv[mm][bj] = *(const u32x4*)(P + row * 4096 + colg + bj * HALF);
;                         if (j > 0) ovv[mm][bj] = *(const u32x4*)(mixed + row * 1024 + colm + bj * HALF); else ovv[mm][bj] = (u32x4){0u, 0u, 0u, 0u}; } }
; #pragma unroll
;                 for (int mm = 0; mm < 2; ++mm) { const int m = 2 * m2 + mm; const size_t row = (size_t)(row0 + ai * HALF + m * 16);
; #pragma unroll
;                     for (int bj = 0; bj < 2; ++bj) {
;                         const u32x4 pv = pvv[mm][bj], ov = ovv[mm][bj];
;                         bf16_t* mp = mixed + row * 1024 + colm + bj * HALF;
;                         const f32x4 a0 = acc[ai][bj][m][0] + bv[bj][0], a1 = acc[ai][bj][m][1] + bv[bj][1];
;                         float r[8];
;                         r[0] = sigmoidf_(a0[0]) * bflo(pv.x); r[1] = sigmoidf_(a0[1]) * bfhi(pv.x); r[2] = sigmoidf_(a0[2]) * bflo(pv.y); r[3] = sigmoidf_(a0[3]) * bfhi(pv.y);
;                         r[4] = sigmoidf_(a1[0]) * bflo(pv.z); r[5] = sigmoidf_(a1[1]) * bfhi(pv.z); r[6] = sigmoidf_(a1[2]) * bflo(pv.w); r[7] = sigmoidf_(a1[3]) * bfhi(pv.w);
;                         r[0] += bflo(ov.x); r[1] += bfhi(ov.x); r[2] += bflo(ov.y); r[3] += bfhi(ov.y); r[4] += bflo(ov.z); r[5] += bfhi(ov.z); r[6] += bflo(ov.w); r[7] += bfhi(ov.w);
;                         u32x4 w; w.x = cvt_pk_bf16(r[0], r[1]); w.y = cvt_pk_bf16(r[2], r[3]); w.z = cvt_pk_bf16(r[4], r[5]); w.w = cvt_pk_bf16(r[6], r[7]);
;                         *(u32x4*)mp = w; } }
	v_lshlrev_b32_e32 v94, 16, v122
	v_and_b32_e32 v95, 0xffff0000, v122
	v_lshlrev_b32_e32 v102, 16, v126
	v_and_b32_e32 v103, 0xffff0000, v126
	v_pk_fma_f32 v[92:93], v[92:93], v[94:95], v[102:103]
	v_pk_add_f32 v[94:95], v[96:97], 1.0 op_sel_hi:[1,0]
	s_nop 0
	s_nop 0
	v_rcp_f32_e32 v95, v95
	s_nop 0
	v_rcp_f32_e32 v94, v94
	v_lshlrev_b32_e32 v96, 16, v123
	v_and_b32_e32 v97, 0xffff0000, v123
	v_lshlrev_b32_e32 v102, 16, v127
	v_and_b32_e32 v103, 0xffff0000, v127
	v_pk_fma_f32 v[94:95], v[94:95], v[96:97], v[102:103]
	v_pk_add_f32 v[96:97], v[100:101], 1.0 op_sel_hi:[1,0]
	s_nop 0
	s_nop 0
	v_rcp_f32_e32 v97, v97
	s_nop 0
	v_rcp_f32_e32 v96, v96
	v_lshlrev_b32_e32 v100, 16, v124
	v_and_b32_e32 v101, 0xffff0000, v124
	v_lshlrev_b32_e32 v102, 16, v128
	v_and_b32_e32 v103, 0xffff0000, v128
	v_pk_fma_f32 v[96:97], v[96:97], v[100:101], v[102:103]
	s_nop 0
	v_rcp_f32_e32 v91, v91
	s_nop 0
	v_rcp_f32_e32 v90, v90
	v_lshlrev_b32_e32 v100, 16, v125
	v_and_b32_e32 v101, 0xffff0000, v125
	v_lshlrev_b32_e32 v102, 16, v129
	v_and_b32_e32 v103, 0xffff0000, v129
	v_pk_fma_f32 v[100:101], v[90:91], v[100:101], v[102:103]
	v_cvt_pk_bf16_f32 v90, v92, v93
	v_cvt_pk_bf16_f32 v91, v94, v95
	v_cvt_pk_bf16_f32 v92, v96, v97
	v_cvt_pk_bf16_f32 v93, v100, v101
	global_store_dwordx4 v[98:99], v[90:93], off
	s_nop 1
	v_exp_f32_e32 v90, v82
	v_mul_f32_e32 v82, 0xbfb8aa3b, v83
	v_exp_f32_e32 v91, v82
	v_mul_f32_e32 v82, 0xbfb8aa3b, v84
	v_mul_f32_e32 v83, 0xbfb8aa3b, v85
	v_pk_add_f32 v[84:85], v[86:87], 1.0 op_sel_hi:[1,0]
	v_exp_f32_e32 v82, v82
	v_exp_f32_e32 v83, v83
	v_rcp_f32_e32 v85, v85
	v_pk_add_f32 v[82:83], v[82:83], 1.0 op_sel_hi:[1,0]
	v_rcp_f32_e32 v84, v84
	s_waitcnt vmcnt(7)
	v_lshlrev_b32_e32 v86, 16, v118
	v_and_b32_e32 v87, 0xffff0000, v118
	v_lshlrev_b32_e32 v92, 16, v114
	v_and_b32_e32 v93, 0xffff0000, v114
	v_pk_fma_f32 v[84:85], v[84:85], v[86:87], v[92:93]
	v_pk_add_f32 v[86:87], v[88:89], 1.0 op_sel_hi:[1,0]
	s_nop 0
	s_nop 0
	v_rcp_f32_e32 v87, v87
	s_nop 0
	v_rcp_f32_e32 v86, v86
	v_lshlrev_b32_e32 v88, 16, v119
	v_and_b32_e32 v89, 0xffff0000, v119
	v_lshlrev_b32_e32 v92, 16, v115
	v_and_b32_e32 v93, 0xffff0000, v115
	v_pk_fma_f32 v[86:87], v[86:87], v[88:89], v[92:93]
	v_pk_add_f32 v[88:89], v[90:91], 1.0 op_sel_hi:[1,0]
	s_nop 0
	s_nop 0
	v_rcp_f32_e32 v89, v89
	s_nop 0
	v_rcp_f32_e32 v88, v88
	v_lshlrev_b32_e32 v90, 16, v120
	v_and_b32_e32 v91, 0xffff0000, v120
	v_lshlrev_b32_e32 v92, 16, v116
	v_and_b32_e32 v93, 0xffff0000, v116
	v_pk_fma_f32 v[88:89], v[88:89], v[90:91], v[92:93]
	s_nop 0
	v_rcp_f32_e32 v83, v83
	s_nop 0
	v_rcp_f32_e32 v82, v82
	v_lshlrev_b32_e32 v90, 16, v121
	v_and_b32_e32 v91, 0xffff0000, v121
	v_lshlrev_b32_e32 v92, 16, v117
	v_and_b32_e32 v93, 0xffff0000, v117
	v_pk_fma_f32 v[90:91], v[82:83], v[90:91], v[92:93]
	v_cvt_pk_bf16_f32 v82, v84, v85
	v_cvt_pk_bf16_f32 v83, v86, v87
	v_cvt_pk_bf16_f32 v84, v88, v89
	v_cvt_pk_bf16_f32 v85, v90, v91
	global_store_dwordx4 v[98:99], v[82:85], off offset:256
	v_mov_b32_e32 v98, 0
	s_and_b64 vcc, exec, s[42:43]
	v_add_u32_e32 v82, 0x80, v206
	v_ashrrev_i32_e32 v83, 31, v82
	v_lshlrev_b64 v[84:85], 13, v[82:83]
	v_lshl_add_u64 v[84:85], v[204:205], 0, v[84:85]
	s_waitcnt vmcnt(4)
	v_mov_b64_e32 v[106:107], v[188:189]
	v_mov_b64_e32 v[108:109], v[190:191]
	v_lshlrev_b64 v[116:117], 11, v[82:83]
	v_lshl_add_u64 v[82:83], v[208:209], 0, v[116:117]
	s_cbranch_vccnz .LBB0_919
	global_load_dwordx4 v[110:113], v[82:83], off
.LBB0_919:
	v_mov_b64_e32 v[102:103], v[232:233]
	v_mov_b64_e32 v[104:105], v[234:235]
	s_and_b64 vcc, exec, s[42:43]
	v_mov_b32_e32 v99, 0
	v_mov_b32_e32 v100, 0
	v_mov_b32_e32 v101, 0
	s_cbranch_vccnz .LBB0_921
	global_load_dwordx4 v[98:101], v[82:83], off offset:256
.LBB0_921:
	v_add_u32_e32 v82, 0x90, v206
	v_ashrrev_i32_e32 v83, 31, v82
	v_lshlrev_b64 v[84:85], 13, v[82:83]
	v_lshl_add_u64 v[84:85], v[204:205], 0, v[84:85]
	v_mov_b64_e32 v[90:91], v[240:241]
	v_mov_b64_e32 v[92:93], v[242:243]
	v_lshlrev_b64 v[114:115], 11, v[82:83]
	v_lshl_add_u64 v[118:119], v[208:209], 0, v[114:115]
	v_mov_b32_e32 v82, 0
	s_and_b64 vcc, exec, s[42:43]
	v_mov_b32_e32 v94, 0
	v_mov_b32_e32 v95, 0
	v_mov_b32_e32 v96, 0
	v_mov_b32_e32 v97, 0
	s_cbranch_vccnz .LBB0_923
	global_load_dwordx4 v[94:97], v[118:119], off
.LBB0_923:
	v_mov_b64_e32 v[86:87], v[244:245]
	v_mov_b64_e32 v[88:89], v[246:247]
	s_and_b64 vcc, exec, s[42:43]
	v_mov_b32_e32 v83, 0
	v_mov_b32_e32 v84, 0
	v_mov_b32_e32 v85, 0
	s_cbranch_vccnz .LBB0_925
	global_load_dwordx4 v[82:85], v[118:119], off offset:256
; __device__ __forceinline__ unsigned cvt_pk_bf16(float lo, float hi) { f32x2_t v = {lo, hi}; bf2_t r = __builtin_convertvector(v, bf2_t); return __builtin_bit_cast(unsigned, r); }
; __device__ __forceinline__ float bflo(unsigned u) { return __uint_as_float(u << 16); }
; __device__ __forceinline__ float bfhi(unsigned u) { return __uint_as_float(u & 0xffff0000u); }
; __device__ __forceinline__ float sigmoidf_(float x) { return 1.0f / (1.0f + __expf(-x)); }
;     __device__ __forceinline__ void operator()(const f32x4 (&acc)[2][2][4][2], const Unit& u, int wr, int wc, int fr, int fq) const {
;     ...
;                 for (int mm = 0; mm < 2; ++mm) { const size_t row = (size_t)(row0 + ai * HALF + (2 * m2 + mm) * 16);
; #pragma unroll
;                     for (int bj = 0; bj < 2; ++bj) { pvv[mm][bj] = *(const u32x4*)(P + row * 4096 + colg + bj * HALF);
;                         if (j > 0) ovv[mm][bj] = *(const u32x4*)(mixed + row * 1024 + colm + bj * HALF); else ovv[mm][bj] = (u32x4){0u, 0u, 0u, 0u}; } }
; #pragma unroll
;                 for (int mm = 0; mm < 2; ++mm) { const int m = 2 * m2 + mm; const size_t row = (size_t)(row0 + ai * HALF + m * 16);
; #pragma unroll
;                     for (int bj = 0; bj < 2; ++bj) {
;                         const u32x4 pv = pvv[mm][bj], ov = ovv[mm][bj];
;                         bf16_t* mp = mixed + row * 1024 + colm + bj * HALF;
;                         const f32x4 a0 = acc[ai][bj][m][0] + bv[bj][0], a1 = acc[ai][bj][m][1] + bv[bj][1];
;                         float r[8];
;                         r[0] = sigmoidf_(a0[0]) * bflo(pv.x); r[1] = sigmoidf_(a0[1]) * bfhi(pv.x); r[2] = sigmoidf_(a0[2]) * bflo(pv.y); r[3] = sigmoidf_(a0[3]) * bfhi(pv.y);
;                         r[4] = sigmoidf_(a1[0]) * bflo(pv.z); r[5] = sigmoidf_(a1[1]) * bfhi(pv.z); r[6] = sigmoidf_(a1[2]) * bflo(pv.w); r[7] = sigmoidf_(a1[3]) * bfhi(pv.w);
;                         r[0] += bflo(ov.x); r[1] += bfhi(ov.x); r[2] += bflo(ov.y); r[3] += bfhi(ov.y); r[4] += bflo(ov.z); r[5] += bfhi(ov.z); r[6] += bflo(ov.w); r[7] += bfhi(ov.w);
;                         u32x4 w; w.x = cvt_pk_bf16(r[0], r[1]); w.y = cvt_pk_bf16(r[2], r[3]); w.z = cvt_pk_bf16(r[4], r[5]); w.w = cvt_pk_bf16(r[6], r[7]);
;                         *(u32x4*)mp = w; } }
.LBB0_925:
	v_add_u32_e32 v236, 0xa0, v206
	v_ashrrev_i32_e32 v237, 31, v236
	v_lshlrev_b64 v[236:237], 13, v[236:237]
	v_lshl_add_u64 v[236:237], v[204:205], 0, v[236:237]
	global_load_dwordx4 v[188:191], v[236:237], off
	global_load_dwordx4 v[232:235], v[236:237], off offset:256
	v_add_u32_e32 v248, 0xb0, v206
	v_ashrrev_i32_e32 v249, 31, v248
	v_lshlrev_b64 v[248:249], 13, v[248:249]
	v_lshl_add_u64 v[248:249], v[204:205], 0, v[248:249]
	global_load_dwordx4 v[240:243], v[248:249], off
	global_load_dwordx4 v[244:247], v[248:249], off offset:256
	v_pk_add_f32 v[78:79], v[78:79], v[40:41]
	v_pk_add_f32 v[74:75], v[74:75], v[32:33]
	v_mul_f32_e32 v78, 0xbfb8aa3b, v78
	v_mul_f32_e32 v79, 0xbfb8aa3b, v79
	v_exp_f32_e32 v78, v78
	v_exp_f32_e32 v79, v79
	v_mul_f32_e32 v74, 0xbfb8aa3b, v74
	v_pk_add_f32 v[76:77], v[76:77], v[34:35]
	v_exp_f32_e32 v118, v74
	v_mul_f32_e32 v74, 0xbfb8aa3b, v75
	v_exp_f32_e32 v119, v74
	v_mul_f32_e32 v74, 0xbfb8aa3b, v76
	v_mul_f32_e32 v75, 0xbfb8aa3b, v77
	v_pk_add_f32 v[76:77], v[78:79], 1.0 op_sel_hi:[1,0]
	v_pk_add_f32 v[80:81], v[80:81], v[42:43]
	v_mul_f32_e32 v80, 0xbfb8aa3b, v80
	v_mul_f32_e32 v81, 0xbfb8aa3b, v81
	v_exp_f32_e32 v80, v80
	v_rcp_f32_e32 v77, v77
	v_exp_f32_e32 v81, v81
	v_exp_f32_e32 v74, v74
	v_exp_f32_e32 v75, v75
	v_rcp_f32_e32 v76, v76
	s_waitcnt vmcnt(7)
	v_lshlrev_b32_e32 v78, 16, v106
	v_and_b32_e32 v79, 0xffff0000, v106
	v_lshlrev_b32_e32 v120, 16, v110
	v_and_b32_e32 v121, 0xffff0000, v110
	v_pk_fma_f32 v[76:77], v[76:77], v[78:79], v[120:121]
	v_pk_add_f32 v[78:79], v[80:81], 1.0 op_sel_hi:[1,0]
	v_pk_add_f32 v[74:75], v[74:75], 1.0 op_sel_hi:[1,0]
	v_pk_add_f32 v[70:71], v[70:71], v[28:29]
	v_lshl_add_u64 v[116:117], s[6:7], 0, v[116:117]
	v_mul_f32_e32 v70, 0xbfb8aa3b, v70
	v_rcp_f32_e32 v79, v79
	v_mul_f32_e32 v71, 0xbfb8aa3b, v71
	v_exp_f32_e32 v70, v70
	v_exp_f32_e32 v71, v71
	v_rcp_f32_e32 v78, v78
	v_lshlrev_b32_e32 v80, 16, v107
	v_and_b32_e32 v81, 0xffff0000, v107
	v_lshlrev_b32_e32 v106, 16, v111
	v_and_b32_e32 v107, 0xffff0000, v111
	v_pk_fma_f32 v[78:79], v[78:79], v[80:81], v[106:107]
	v_pk_add_f32 v[80:81], v[118:119], 1.0 op_sel_hi:[1,0]
	v_pk_add_f32 v[66:67], v[66:67], v[24:25]
	v_lshl_add_u64 v[116:117], v[116:117], 0, v[64:65]
	v_mul_f32_e32 v66, 0xbfb8aa3b, v66
	v_pk_add_f32 v[68:69], v[68:69], v[26:27]
	v_rcp_f32_e32 v81, v81
	v_pk_add_f32 v[72:73], v[72:73], v[30:31]
	v_pk_add_f32 v[60:61], v[60:61], v[40:41]
	v_mul_f32_e32 v72, 0xbfb8aa3b, v72
	v_rcp_f32_e32 v80, v80
	v_lshlrev_b32_e32 v106, 16, v108
	v_and_b32_e32 v107, 0xffff0000, v108
	v_lshlrev_b32_e32 v110, 16, v112
	v_and_b32_e32 v111, 0xffff0000, v112
	v_pk_fma_f32 v[80:81], v[80:81], v[106:107], v[110:111]
	v_mul_f32_e32 v73, 0xbfb8aa3b, v73
	v_exp_f32_e32 v72, v72
	v_exp_f32_e32 v73, v73
	v_rcp_f32_e32 v75, v75
	v_mul_f32_e32 v60, 0xbfb8aa3b, v60
	v_mul_f32_e32 v61, 0xbfb8aa3b, v61
	v_exp_f32_e32 v60, v60
	v_rcp_f32_e32 v74, v74
	v_lshlrev_b32_e32 v106, 16, v109
	v_and_b32_e32 v107, 0xffff0000, v109
	v_lshlrev_b32_e32 v108, 16, v113
	v_and_b32_e32 v109, 0xffff0000, v113
	v_pk_fma_f32 v[106:107], v[74:75], v[106:107], v[108:109]
	v_cvt_pk_bf16_f32 v74, v76, v77
	v_cvt_pk_bf16_f32 v75, v78, v79
	v_cvt_pk_bf16_f32 v76, v80, v81
	v_cvt_pk_bf16_f32 v77, v106, v107
	global_store_dwordx4 v[116:117], v[74:77], off
	v_exp_f32_e32 v61, v61
	v_pk_add_f32 v[56:57], v[56:57], v[32:33]
	v_exp_f32_e32 v74, v66
	v_mul_f32_e32 v66, 0xbfb8aa3b, v67
	v_exp_f32_e32 v75, v66
	v_mul_f32_e32 v66, 0xbfb8aa3b, v68
	v_mul_f32_e32 v67, 0xbfb8aa3b, v69
	v_pk_add_f32 v[68:69], v[70:71], 1.0 op_sel_hi:[1,0]
	v_exp_f32_e32 v66, v66
	v_exp_f32_e32 v67, v67
	v_mul_f32_e32 v56, 0xbfb8aa3b, v56
	v_pk_add_f32 v[58:59], v[58:59], v[34:35]
	v_rcp_f32_e32 v69, v69
	v_pk_add_f32 v[66:67], v[66:67], 1.0 op_sel_hi:[1,0]
	v_pk_add_f32 v[62:63], v[62:63], v[42:43]
	v_pk_add_f32 v[52:53], v[52:53], v[28:29]
	v_rcp_f32_e32 v68, v68
	s_waitcnt vmcnt(7)
	v_lshlrev_b32_e32 v70, 16, v102
	v_and_b32_e32 v71, 0xffff0000, v102
	v_lshlrev_b32_e32 v76, 16, v98
	v_and_b32_e32 v77, 0xffff0000, v98
	v_pk_fma_f32 v[68:69], v[68:69], v[70:71], v[76:77]
	v_pk_add_f32 v[70:71], v[72:73], 1.0 op_sel_hi:[1,0]
	v_mul_f32_e32 v62, 0xbfb8aa3b, v62
	v_mul_f32_e32 v63, 0xbfb8aa3b, v63
	v_exp_f32_e32 v62, v62
	v_exp_f32_e32 v63, v63
	v_rcp_f32_e32 v71, v71
	v_mul_f32_e32 v52, 0xbfb8aa3b, v52
	v_mul_f32_e32 v53, 0xbfb8aa3b, v53
	v_exp_f32_e32 v52, v52
	v_rcp_f32_e32 v70, v70
	v_lshlrev_b32_e32 v72, 16, v103
	v_and_b32_e32 v73, 0xffff0000, v103
	v_lshlrev_b32_e32 v76, 16, v99
	v_and_b32_e32 v77, 0xffff0000, v99
	v_pk_fma_f32 v[70:71], v[70:71], v[72:73], v[76:77]
	v_pk_add_f32 v[72:73], v[74:75], 1.0 op_sel_hi:[1,0]
	v_exp_f32_e32 v53, v53
	v_pk_add_f32 v[48:49], v[48:49], v[24:25]
	v_pk_add_f32 v[50:51], v[50:51], v[26:27]
	v_mul_f32_e32 v48, 0xbfb8aa3b, v48
	v_rcp_f32_e32 v73, v73
	v_pk_add_f32 v[54:55], v[54:55], v[30:31]
	v_mov_b32_e32 v79, 0
	v_mul_f32_e32 v54, 0xbfb8aa3b, v54
	v_rcp_f32_e32 v72, v72
	v_lshlrev_b32_e32 v74, 16, v104
	v_and_b32_e32 v75, 0xffff0000, v104
	v_lshlrev_b32_e32 v76, 16, v100
	v_and_b32_e32 v77, 0xffff0000, v100
	v_pk_fma_f32 v[72:73], v[72:73], v[74:75], v[76:77]
	v_mul_f32_e32 v55, 0xbfb8aa3b, v55
	v_exp_f32_e32 v54, v54
	v_exp_f32_e32 v55, v55
	v_rcp_f32_e32 v67, v67
	v_mov_b32_e32 v80, 0
	v_mov_b32_e32 v81, 0
	v_rcp_f32_e32 v66, v66
	v_lshlrev_b32_e32 v74, 16, v105
	v_and_b32_e32 v75, 0xffff0000, v105
	v_lshlrev_b32_e32 v76, 16, v101
	v_and_b32_e32 v77, 0xffff0000, v101
	v_pk_fma_f32 v[74:75], v[66:67], v[74:75], v[76:77]
	v_cvt_pk_bf16_f32 v66, v68, v69
	v_cvt_pk_bf16_f32 v67, v70, v71
	v_cvt_pk_bf16_f32 v68, v72, v73
	v_cvt_pk_bf16_f32 v69, v74, v75
	global_store_dwordx4 v[116:117], v[66:69], off offset:256
	v_mov_b32_e32 v78, 0
	s_nop 0
	v_exp_f32_e32 v68, v56
	v_mul_f32_e32 v56, 0xbfb8aa3b, v57
	v_exp_f32_e32 v69, v56
	v_mul_f32_e32 v56, 0xbfb8aa3b, v58
	v_mul_f32_e32 v57, 0xbfb8aa3b, v59
	v_pk_add_f32 v[58:59], v[60:61], 1.0 op_sel_hi:[1,0]
	v_exp_f32_e32 v56, v56
	v_exp_f32_e32 v57, v57
	v_lshl_add_u64 v[66:67], s[6:7], 0, v[114:115]
	v_lshl_add_u64 v[66:67], v[66:67], 0, v[64:65]
	v_rcp_f32_e32 v59, v59
	v_pk_add_f32 v[56:57], v[56:57], 1.0 op_sel_hi:[1,0]
	v_rcp_f32_e32 v58, v58
	s_waitcnt vmcnt(7)
; __device__ __forceinline__ unsigned cvt_pk_bf16(float lo, float hi) { f32x2_t v = {lo, hi}; bf2_t r = __builtin_convertvector(v, bf2_t); return __builtin_bit_cast(unsigned, r); }
; __device__ __forceinline__ float bflo(unsigned u) { return __uint_as_float(u << 16); }
; __device__ __forceinline__ float bfhi(unsigned u) { return __uint_as_float(u & 0xffff0000u); }
; __device__ __forceinline__ float sigmoidf_(float x) { return 1.0f / (1.0f + __expf(-x)); }
;     __device__ __forceinline__ void operator()(const f32x4 (&acc)[2][2][4][2], const Unit& u, int wr, int wc, int fr, int fq) const {
;     ...
;                 for (int mm = 0; mm < 2; ++mm) { const size_t row = (size_t)(row0 + ai * HALF + (2 * m2 + mm) * 16);
; #pragma unroll
;                     for (int bj = 0; bj < 2; ++bj) { pvv[mm][bj] = *(const u32x4*)(P + row * 4096 + colg + bj * HALF);
;                         if (j > 0) ovv[mm][bj] = *(const u32x4*)(mixed + row * 1024 + colm + bj * HALF); else ovv[mm][bj] = (u32x4){0u, 0u, 0u, 0u}; } }
; #pragma unroll
;                 for (int mm = 0; mm < 2; ++mm) { const int m = 2 * m2 + mm; const size_t row = (size_t)(row0 + ai * HALF + m * 16);
; #pragma unroll
;                     for (int bj = 0; bj < 2; ++bj) {
;                         const u32x4 pv = pvv[mm][bj], ov = ovv[mm][bj];
;                         bf16_t* mp = mixed + row * 1024 + colm + bj * HALF;
;                         const f32x4 a0 = acc[ai][bj][m][0] + bv[bj][0], a1 = acc[ai][bj][m][1] + bv[bj][1];
;                         float r[8];
;                         r[0] = sigmoidf_(a0[0]) * bflo(pv.x); r[1] = sigmoidf_(a0[1]) * bfhi(pv.x); r[2] = sigmoidf_(a0[2]) * bflo(pv.y); r[3] = sigmoidf_(a0[3]) * bfhi(pv.y);
;                         r[4] = sigmoidf_(a1[0]) * bflo(pv.z); r[5] = sigmoidf_(a1[1]) * bfhi(pv.z); r[6] = sigmoidf_(a1[2]) * bflo(pv.w); r[7] = sigmoidf_(a1[3]) * bfhi(pv.w);
;                         r[0] += bflo(ov.x); r[1] += bfhi(ov.x); r[2] += bflo(ov.y); r[3] += bfhi(ov.y); r[4] += bflo(ov.z); r[5] += bfhi(ov.z); r[6] += bflo(ov.w); r[7] += bfhi(ov.w);
;                         u32x4 w; w.x = cvt_pk_bf16(r[0], r[1]); w.y = cvt_pk_bf16(r[2], r[3]); w.z = cvt_pk_bf16(r[4], r[5]); w.w = cvt_pk_bf16(r[6], r[7]);
;                         *(u32x4*)mp = w; } }
	v_lshlrev_b32_e32 v60, 16, v90
	v_and_b32_e32 v61, 0xffff0000, v90
	v_lshlrev_b32_e32 v70, 16, v94
	v_and_b32_e32 v71, 0xffff0000, v94
	v_pk_fma_f32 v[58:59], v[58:59], v[60:61], v[70:71]
	v_pk_add_f32 v[60:61], v[62:63], 1.0 op_sel_hi:[1,0]
	s_nop 0
	s_nop 0
	v_rcp_f32_e32 v61, v61
	s_nop 0
	v_rcp_f32_e32 v60, v60
	v_lshlrev_b32_e32 v62, 16, v91
	v_and_b32_e32 v63, 0xffff0000, v91
	v_lshlrev_b32_e32 v70, 16, v95
	v_and_b32_e32 v71, 0xffff0000, v95
	v_pk_fma_f32 v[60:61], v[60:61], v[62:63], v[70:71]
	v_pk_add_f32 v[62:63], v[68:69], 1.0 op_sel_hi:[1,0]
	s_nop 0
	s_nop 0
	v_rcp_f32_e32 v63, v63
	s_nop 0
	v_rcp_f32_e32 v62, v62
	v_lshlrev_b32_e32 v68, 16, v92
	v_and_b32_e32 v69, 0xffff0000, v92
	v_lshlrev_b32_e32 v70, 16, v96
	v_and_b32_e32 v71, 0xffff0000, v96
	v_pk_fma_f32 v[62:63], v[62:63], v[68:69], v[70:71]
	s_nop 0
	v_rcp_f32_e32 v57, v57
	s_nop 0
	v_rcp_f32_e32 v56, v56
	v_lshlrev_b32_e32 v68, 16, v93
	v_and_b32_e32 v69, 0xffff0000, v93
	v_lshlrev_b32_e32 v70, 16, v97
	v_and_b32_e32 v71, 0xffff0000, v97
	v_pk_fma_f32 v[68:69], v[56:57], v[68:69], v[70:71]
	v_cvt_pk_bf16_f32 v56, v58, v59
	v_cvt_pk_bf16_f32 v57, v60, v61
	v_cvt_pk_bf16_f32 v58, v62, v63
	v_cvt_pk_bf16_f32 v59, v68, v69
	global_store_dwordx4 v[66:67], v[56:59], off
	s_nop 1
	v_exp_f32_e32 v56, v48
	v_mul_f32_e32 v48, 0xbfb8aa3b, v49
	v_exp_f32_e32 v57, v48
	v_mul_f32_e32 v48, 0xbfb8aa3b, v50
	v_mul_f32_e32 v49, 0xbfb8aa3b, v51
	v_pk_add_f32 v[50:51], v[52:53], 1.0 op_sel_hi:[1,0]
	v_exp_f32_e32 v48, v48
	v_exp_f32_e32 v49, v49
	v_rcp_f32_e32 v51, v51
	v_pk_add_f32 v[48:49], v[48:49], 1.0 op_sel_hi:[1,0]
	v_rcp_f32_e32 v50, v50
	s_waitcnt vmcnt(7)
	v_lshlrev_b32_e32 v52, 16, v86
	v_and_b32_e32 v53, 0xffff0000, v86
	v_lshlrev_b32_e32 v58, 16, v82
	v_and_b32_e32 v59, 0xffff0000, v82
	v_pk_fma_f32 v[50:51], v[50:51], v[52:53], v[58:59]
	v_pk_add_f32 v[52:53], v[54:55], 1.0 op_sel_hi:[1,0]
	s_nop 0
	s_nop 0
	v_rcp_f32_e32 v53, v53
	s_nop 0
	v_rcp_f32_e32 v52, v52
	v_lshlrev_b32_e32 v54, 16, v87
	v_and_b32_e32 v55, 0xffff0000, v87
	v_lshlrev_b32_e32 v58, 16, v83
	v_and_b32_e32 v59, 0xffff0000, v83
	v_pk_fma_f32 v[52:53], v[52:53], v[54:55], v[58:59]
	v_pk_add_f32 v[54:55], v[56:57], 1.0 op_sel_hi:[1,0]
	s_nop 0
	s_nop 0
	v_rcp_f32_e32 v55, v55
	s_nop 0
	v_rcp_f32_e32 v54, v54
	v_lshlrev_b32_e32 v56, 16, v88
	v_and_b32_e32 v57, 0xffff0000, v88
	v_lshlrev_b32_e32 v58, 16, v84
	v_and_b32_e32 v59, 0xffff0000, v84
	v_pk_fma_f32 v[54:55], v[54:55], v[56:57], v[58:59]
	s_nop 0
	v_rcp_f32_e32 v49, v49
	s_nop 0
	v_rcp_f32_e32 v48, v48
	v_lshlrev_b32_e32 v56, 16, v89
	v_and_b32_e32 v57, 0xffff0000, v89
	v_lshlrev_b32_e32 v58, 16, v85
	v_and_b32_e32 v59, 0xffff0000, v85
	v_pk_fma_f32 v[56:57], v[48:49], v[56:57], v[58:59]
	v_cvt_pk_bf16_f32 v48, v50, v51
	v_cvt_pk_bf16_f32 v49, v52, v53
	v_cvt_pk_bf16_f32 v50, v54, v55
	v_cvt_pk_bf16_f32 v51, v56, v57
	global_store_dwordx4 v[66:67], v[48:51], off offset:256
	v_mov_b32_e32 v66, 0
	s_and_b64 vcc, exec, s[42:43]
	v_add_u32_e32 v48, 0xa0, v206
	v_ashrrev_i32_e32 v49, 31, v48
	v_lshlrev_b64 v[50:51], 13, v[48:49]
	v_lshl_add_u64 v[50:51], v[204:205], 0, v[50:51]
	s_waitcnt vmcnt(4)
	v_mov_b64_e32 v[74:75], v[188:189]
	v_mov_b64_e32 v[76:77], v[190:191]
	v_lshlrev_b64 v[84:85], 11, v[48:49]
	v_lshl_add_u64 v[48:49], v[208:209], 0, v[84:85]
	s_cbranch_vccnz .LBB0_927
	global_load_dwordx4 v[78:81], v[48:49], off
.LBB0_927:
	v_mov_b64_e32 v[70:71], v[232:233]
	v_mov_b64_e32 v[72:73], v[234:235]
	s_and_b64 vcc, exec, s[42:43]
	v_mov_b32_e32 v67, 0
	v_mov_b32_e32 v68, 0
	v_mov_b32_e32 v69, 0
	s_cbranch_vccnz .LBB0_929
	global_load_dwordx4 v[66:69], v[48:49], off offset:256
.LBB0_929:
	v_add_u32_e32 v48, 0xb0, v206
	v_ashrrev_i32_e32 v49, 31, v48
	v_lshlrev_b64 v[50:51], 13, v[48:49]
	v_lshl_add_u64 v[50:51], v[204:205], 0, v[50:51]
	v_mov_b64_e32 v[56:57], v[240:241]
	v_mov_b64_e32 v[58:59], v[242:243]
	v_lshlrev_b64 v[82:83], 11, v[48:49]
	v_lshl_add_u64 v[86:87], v[208:209], 0, v[82:83]
	v_mov_b32_e32 v48, 0
	s_and_b64 vcc, exec, s[42:43]
	v_mov_b32_e32 v60, 0
	v_mov_b32_e32 v61, 0
	v_mov_b32_e32 v62, 0
	v_mov_b32_e32 v63, 0
	s_cbranch_vccnz .LBB0_931
	global_load_dwordx4 v[60:63], v[86:87], off
.LBB0_931:
	v_mov_b64_e32 v[52:53], v[244:245]
	v_mov_b64_e32 v[54:55], v[246:247]
	s_and_b64 vcc, exec, s[42:43]
	v_mov_b32_e32 v49, 0
	v_mov_b32_e32 v50, 0
	v_mov_b32_e32 v51, 0
	s_cbranch_vccnz .LBB0_933
	global_load_dwordx4 v[48:51], v[86:87], off offset:256
